# cross-attn V tile row-major + transpose reads (removes 16-way LDS write conflicts); MLA: fused softmax+PV block, K-fragment prefetch, heaviest query tiles as 128-query half units
# speedup vs baseline: 1.0547x; 1.0129x over previous
; template <int MODE>
; DI void attn_unit(LAS unsigned char* lds, const AttnArgs a) {
;     ...
;     ATT_LOAD(it0);
;     ATT_STORE(0);
;     __syncthreads();
.LBB0_51:
	s_or_b64 exec, exec, s[18:19]
	v_lshrrev_b32_e32 v171, 2, v0
	v_and_b32_e32 v172, 3, v18
	v_xor_b32_e32 v171, v171, v172
	v_lshlrev_b32_e32 v171, 6, v171
	v_and_b32_e32 v172, 3, v0
	v_lshl_add_u32 v171, v172, 4, v171
	v_lshl_add_u32 v171, v18, 8, v171
	v_mov_b32_e32 v172, 0
	s_movk_i32 s18, 0x100
	v_add_u32_e32 v0, s18, v171
	s_waitcnt vmcnt(0)
	ds_write_b128 v0, v[6:9] offset:17408
	ds_write_b128 v0, v[2:5] offset:25600
	s_waitcnt lgkmcnt(0)
	s_barrier
	s_and_saveexec_b64 s[18:19], s[8:9]
	s_cbranch_execz .LBB0_53
	v_lshlrev_b64 v[2:3], 11, v[18:19]
	v_lshl_add_u64 v[2:3], s[16:17], 0, v[2:3]
	v_lshl_add_u64 v[2:3], v[20:21], 1, v[2:3]
	v_add_co_u32_e32 v2, vcc, 0x20000, v2
	s_nop 1
	v_addc_co_u32_e32 v3, vcc, 0, v3, vcc
	global_load_dwordx4 v[144:147], v[2:3], off

; #define LAS __attribute__((address_space(3)))
; template <int MODE>
; DI void attn_unit(LAS unsigned char* lds, const AttnArgs a) {
;     ...
;     f32x16 o[NDB];
; #pragma unroll
;     for (int d = 0; d < NDB; ++d)
; #pragma unroll
;         for (int i = 0; i < 16; ++i) o[d][i] = 0.f;
;     float mrow = -1e30f, lrow = 0.f, carry = 1.f;
;     int ntile;
;     if (MODE == 0) ntile = a.nk / 64; else if (MODE == 1) ntile = (a.q0 + 255) / 64 + 1; else if (MODE == 2) ntile = (a.q0 + 254) / 64 + 1; else ntile = 6;
;     const int it0 = (MODE == 3 && a.q0 == 0) ? 2 : 0;
;     constexpr int NKC = (64 * (DK / 8) + 511) / 512, NVC = (64 * (DV / 8) + 511) / 512;
;     u32x4 kreg[NKC], vreg[NVC];
;     ...
;     ATT_LOAD(it0);
;     ATT_STORE(0);
;     __syncthreads();
;     if (it0 + 1 < ntile) ATT_LOAD(it0 + 1);
;     bool sb_dead = false;
;     for (int it = it0; it < ntile; ++it) {
;         const int kbase = ATT_KBASE(it), cur = (it - it0) & 1;
;         const LAS bf16_t* Kc = Ks + cur * BUFE; const LAS bf16_t* Vc = Vt + cur * BUFE;
;         bool active = true;
;         if (MODE == 1) active = kbase <= q0w + 31;
;         if (MODE == 2) active = (kbase <= q0w + 30) && !sb_dead;
.LBB0_55:
	s_or_b64 exec, exec, s[18:19]
	v_lshlrev_b64 v[6:7], 11, v[18:19]
	v_lshl_add_u64 v[6:7], s[16:17], 0, v[6:7]
	v_lshlrev_b64 v[8:9], 1, v[20:21]
	v_lshl_add_u64 v[6:7], v[6:7], 0, v[8:9]
	v_add_co_u32_e32 v6, vcc, 0x20000, v6
	v_lshlrev_b64 v[12:13], 1, v[12:13]
	s_nop 0
	v_addc_co_u32_e32 v7, vcc, 0, v7, vcc
	v_lshl_add_u64 v[4:5], v[4:5], 0, v[12:13]
	global_load_dwordx4 v[152:155], v[6:7], off offset:1024
	global_load_dwordx4 v[156:159], v[4:5], off offset:1024
	s_lshl_b32 s16, s4, 1
	s_lshl_b64 s[12:13], s[12:13], 21
	s_and_b32 s16, s16, 0x300
	v_lshlrev_b32_e32 v160, 3, v23
	v_mul_u32_u24_e32 v4, 0x90, v22
	s_movk_i32 s17, 0x100
	s_add_u32 s14, s16, s14
	v_mul_u32_u24_e32 v0, 0x110, v22
	v_add3_u32 v175, s17, v160, v4
	v_bfe_u32 v175, v22, 2, 2
	v_mul_u32_u24_e32 v175, 0x140, v175
	v_and_b32_e32 v179, 3, v22
	v_lshl_add_u32 v175, v179, 3, v175
	v_bfe_u32 v179, v22, 4, 1
	v_lshl_add_u32 v175, v179, 5, v175
	v_lshl_add_u32 v175, v23, 10, v175
	v_add_u32_e32 v175, 0x4500, v175
	v_lshlrev_b32_e32 v4, 1, v160
	s_addc_u32 s15, 0, s15
	v_add3_u32 v176, s17, v0, v4
	v_lshl_add_u64 v[4:5], s[14:15], 0, v[16:17]
	v_lshl_add_u64 v[2:3], s[14:15], 0, v[2:3]
	v_lshl_add_u64 v[4:5], v[4:5], 0, v[8:9]
	v_lshl_add_u64 v[2:3], v[2:3], 0, v[12:13]
	v_mov_b32_e32 v14, v1
	v_mov_b32_e32 v15, v1
	v_lshlrev_b64 v[162:163], 9, v[10:11]
	v_lshl_add_u64 v[164:165], s[6:7], 0, v[4:5]
	v_lshl_add_u64 v[166:167], s[6:7], 0, v[2:3]
	v_mov_b32_e32 v0, v1
	v_mov_b32_e32 v2, v1
	v_mov_b32_e32 v3, v1
	v_mov_b32_e32 v4, v1
	v_mov_b32_e32 v5, v1
	v_mov_b32_e32 v6, v1
	v_mov_b32_e32 v7, v1
	v_mov_b32_e32 v8, v1
	v_mov_b32_e32 v9, v1
	v_mov_b32_e32 v10, v1
	v_mov_b32_e32 v11, v1
	v_mov_b32_e32 v12, v1
	v_mov_b32_e32 v13, v1
	v_mov_b64_e32 v[30:31], v[14:15]
	v_mov_b64_e32 v[46:47], v[14:15]
	v_mov_b64_e32 v[62:63], v[14:15]
	v_mov_b64_e32 v[78:79], v[14:15]
	s_mov_b32 s18, 0
	v_mov_b32_e32 v178, 0
	v_mov_b32_e32 v177, 0xf149f2ca
	s_mov_b64 s[14:15], 0
	v_mov_b64_e32 v[28:29], v[12:13]
	v_mov_b64_e32 v[26:27], v[10:11]
	v_mov_b64_e32 v[24:25], v[8:9]
	v_mov_b64_e32 v[22:23], v[6:7]
	v_mov_b64_e32 v[20:21], v[4:5]
	v_mov_b64_e32 v[18:19], v[2:3]
	v_mov_b64_e32 v[16:17], v[0:1]
	v_mov_b64_e32 v[44:45], v[12:13]
	v_mov_b64_e32 v[42:43], v[10:11]
	v_mov_b64_e32 v[40:41], v[8:9]
	v_mov_b64_e32 v[38:39], v[6:7]
	v_mov_b64_e32 v[36:37], v[4:5]
	v_mov_b64_e32 v[34:35], v[2:3]
	v_mov_b64_e32 v[32:33], v[0:1]
	v_mov_b64_e32 v[60:61], v[12:13]
	v_mov_b64_e32 v[58:59], v[10:11]
	v_mov_b64_e32 v[56:57], v[8:9]
	v_mov_b64_e32 v[54:55], v[6:7]
	v_mov_b64_e32 v[52:53], v[4:5]
	v_mov_b64_e32 v[50:51], v[2:3]
	v_mov_b64_e32 v[48:49], v[0:1]
	v_mov_b64_e32 v[76:77], v[12:13]
	v_mov_b64_e32 v[74:75], v[10:11]
	v_mov_b64_e32 v[72:73], v[8:9]
	v_mov_b64_e32 v[70:71], v[6:7]
	v_mov_b64_e32 v[68:69], v[4:5]
	v_mov_b64_e32 v[66:67], v[2:3]
	v_mov_b64_e32 v[64:65], v[0:1]

; template <int MODE>
; DI void attn_unit(LAS unsigned char* lds, const AttnArgs a) {
;     ...
; #pragma unroll
;                 for (int i = 0; i < 16; ++i) {
;                     const float p0 = ex2(s0[i] - mnew), p1 = ex2(s1[i] - mnew);
;                     s0[i] = p0; s1[i] = p1; ls += p0 + p1;
;                 }
;             } else {
;                 float mx = -1e30f;
; #pragma unroll
;                 for (int i = 0; i < 16; ++i) {
;                     const int k0 = kbase + crow(i, hh), k1 = k0 + 32;
;                     float x0 = s0[i] * a.c2, x1 = s1[i] * a.c2;
;                     bool v0 = true, v1 = true;
;                     if (MODE == 1) { v0 = k0 <= qi; v1 = k1 <= qi; }
;                     if (MODE == 3) {
;                         const int st0 = qi - k0, st1 = qi - k1;
;                         v0 = (st0 >= 0) && (st0 <= 128) && (k0 >= 0); v1 = (st1 >= 0) && (st1 <= 128) && (k1 >= 0);
;                         x0 += biasL[min(max(st0, 0), 128)]; x1 += biasL[min(max(st1, 0), 128)];
;                     }
;                     x0 = v0 ? x0 : -1e30f; x1 = v1 ? x1 : -1e30f;
;                     s0[i] = x0; s1[i] = x1; mx = fmaxf(mx, fmaxf(x0, x1));
;                 }
;                 mx = fmaxf(mx, __shfl_xor(mx, 32));
;                 mnew = fmaxf(mrow, mx); alpha = ex2(mrow - mnew);
; #pragma unroll
;                 for (int i = 0; i < 16; ++i) {
;                     const float p0 = (s0[i] > -1e29f) ? ex2(s0[i] - mnew) : 0.f, p1 = (s1[i] > -1e29f) ? ex2(s1[i] - mnew) : 0.f;
;                     s0[i] = p0; s1[i] = p1; ls += p0 + p1;
;                 }
;             }
;             mrow = mnew;
;             lrow = lrow * alpha + ls;
;             if (__ballot(alpha < 1.0f) != 0ull) {
; #pragma unroll
;                 for (int d = 0; d < NDB; ++d)
; #pragma unroll
;                     for (int i = 0; i < 16; ++i) o[d][i] *= alpha;
;             }
;         }
;         const bf16x8 pb00 = pack8(s0, 0), pb01 = pack8(s0, 1), pb10 = pack8(s1, 0), pb11 = pack8(s1, 1);
; #pragma unroll
;         for (int d = 0; d < NDB; ++d) {
;             const LAS bf16_t* vp = Vc + (d * 32 + r32) * VLD;
;             const int sw = SWZ ? ((((d * 32 + r32) >> 3) & 7) << 2) : 0;
;     ...
;             o[d] = MFMA32(VFRAG(0), pb00, o[d]);
;             o[d] = MFMA32(VFRAG(16), pb01, o[d]);
;             o[d] = MFMA32(VFRAG(32), pb10, o[d]);
.LBB0_58:
	v_sub_f32_e32 v4, v4, v177
	v_exp_f32_e32 v5, v4
	v_sub_f32_e32 v4, v9, v177
	v_exp_f32_e32 v9, v4
	v_sub_f32_e32 v4, v179, v177
	v_lshl_add_u32 v179, s17, 1, v175
	v_sub_f32_e32 v95, v99, v177
	v_mov_b32_e32 v99, v179
	v_sub_f32_e32 v89, v102, v177
	v_sub_f32_e32 v91, v101, v177
	v_sub_f32_e32 v93, v100, v177
	ds_read_b64_tr_b16 v[100:101], v99 offset:0
	ds_read_b64_tr_b16 v[102:103], v99 offset:2048
	v_sub_f32_e32 v7, v7, v177
	v_sub_f32_e32 v6, v6, v177
	v_sub_f32_e32 v11, v11, v177
	v_sub_f32_e32 v8, v8, v177
	v_sub_f32_e32 v15, v15, v177
	v_sub_f32_e32 v10, v10, v177
	v_exp_f32_e32 v4, v4
	v_exp_f32_e32 v7, v7
	v_exp_f32_e32 v6, v6
	v_exp_f32_e32 v11, v11
	v_exp_f32_e32 v8, v8
	v_exp_f32_e32 v15, v15
	v_exp_f32_e32 v10, v10
	v_cvt_pk_bf16_f32 v104, v5, v4
	v_cvt_pk_bf16_f32 v105, v7, v6
	v_cvt_pk_bf16_f32 v106, v11, v8
	v_cvt_pk_bf16_f32 v107, v15, v10
	ds_read_b64_tr_b16 v[108:109], v99 offset:4096
	ds_read_b64_tr_b16 v[110:111], v99 offset:6144
	v_sub_f32_e32 v83, v83, v177
	s_waitcnt lgkmcnt(2)
	v_mfma_f32_32x32x16_bf16 v[64:79], v[100:103], v[104:107], v[64:79]
	v_sub_f32_e32 v14, v14, v177
	v_sub_f32_e32 v87, v87, v177
	v_sub_f32_e32 v82, v82, v177
	v_sub_f32_e32 v86, v86, v177
	v_sub_f32_e32 v94, v94, v177
	v_sub_f32_e32 v92, v92, v177
	v_exp_f32_e32 v83, v83
	v_exp_f32_e32 v14, v14
	v_exp_f32_e32 v87, v87
	v_exp_f32_e32 v82, v82
	v_exp_f32_e32 v93, v93
	v_exp_f32_e32 v86, v86
	v_sub_f32_e32 v184, v97, v177
	v_exp_f32_e32 v97, v94
	v_exp_f32_e32 v92, v92
	v_cvt_pk_bf16_f32 v180, v83, v14
	v_cvt_pk_bf16_f32 v181, v87, v82
	v_cvt_pk_bf16_f32 v182, v93, v86
	v_cvt_pk_bf16_f32 v183, v97, v92
	ds_read_b64_tr_b16 v[100:101], v99 offset:8192
	ds_read_b64_tr_b16 v[102:103], v99 offset:10240
	v_sub_f32_e32 v0, v0, v177
	s_waitcnt lgkmcnt(2)
	v_mfma_f32_32x32x16_bf16 v[64:79], v[108:111], v[180:183], v[64:79]
	v_sub_f32_e32 v13, v13, v177
	v_sub_f32_e32 v12, v12, v177
	v_sub_f32_e32 v81, v81, v177
	v_sub_f32_e32 v80, v80, v177
	v_sub_f32_e32 v85, v85, v177
	v_sub_f32_e32 v84, v84, v177
	v_exp_f32_e32 v0, v0
	v_exp_f32_e32 v13, v13
	v_exp_f32_e32 v12, v12
	v_exp_f32_e32 v81, v81
	v_exp_f32_e32 v80, v80
	v_exp_f32_e32 v85, v85
	v_exp_f32_e32 v84, v84
	v_exp_f32_e32 v94, v184
	v_cvt_pk_bf16_f32 v108, v9, v0
	v_cvt_pk_bf16_f32 v109, v13, v12
	v_cvt_pk_bf16_f32 v110, v81, v80
	v_cvt_pk_bf16_f32 v111, v85, v84
	ds_read_b64_tr_b16 v[184:185], v99 offset:12288
	ds_read_b64_tr_b16 v[186:187], v99 offset:14336
	v_sub_f32_e32 v88, v88, v177
	s_waitcnt lgkmcnt(2)
	v_mfma_f32_32x32x16_bf16 v[64:79], v[100:103], v[108:111], v[64:79]
	v_sub_f32_e32 v90, v90, v177
	v_sub_f32_e32 v98, v98, v177
	v_sub_f32_e32 v96, v96, v177
	v_exp_f32_e32 v89, v89
	v_exp_f32_e32 v88, v88
	v_exp_f32_e32 v91, v91
	v_exp_f32_e32 v90, v90
	v_exp_f32_e32 v95, v95
	v_exp_f32_e32 v102, v98
	v_exp_f32_e32 v96, v96
	v_cvt_pk_bf16_f32 v98, v89, v88
	v_cvt_pk_bf16_f32 v99, v91, v90
	v_cvt_pk_bf16_f32 v100, v95, v94
	v_cvt_pk_bf16_f32 v101, v102, v96
	v_xor_b32_e32 v103, 64, v179
	s_cmp_gt_u32 s18, 2
	s_waitcnt lgkmcnt(0)
	v_mfma_f32_32x32x16_bf16 v[64:79], v[184:187], v[98:101], v[64:79]
	ds_read_b64_tr_b16 v[184:185], v103 offset:0
	ds_read_b64_tr_b16 v[186:187], v103 offset:2048
	s_waitcnt lgkmcnt(0)
	v_mfma_f32_32x32x16_bf16 v[48:63], v[184:187], v[104:107], v[48:63]
	ds_read_b64_tr_b16 v[184:185], v103 offset:4096
	ds_read_b64_tr_b16 v[186:187], v103 offset:6144
	s_waitcnt lgkmcnt(0)
	v_mfma_f32_32x32x16_bf16 v[48:63], v[184:187], v[180:183], v[48:63]
	ds_read_b64_tr_b16 v[184:185], v103 offset:8192
	ds_read_b64_tr_b16 v[186:187], v103 offset:10240
	s_waitcnt lgkmcnt(0)
	v_mfma_f32_32x32x16_bf16 v[48:63], v[184:187], v[108:111], v[48:63]
	ds_read_b64_tr_b16 v[184:185], v103 offset:12288
	ds_read_b64_tr_b16 v[186:187], v103 offset:14336
	v_xor_b32_e32 v103, 0x80, v179
	s_waitcnt lgkmcnt(0)
	v_mfma_f32_32x32x16_bf16 v[48:63], v[184:187], v[98:101], v[48:63]
	ds_read_b64_tr_b16 v[184:185], v103 offset:0
	ds_read_b64_tr_b16 v[186:187], v103 offset:2048
	s_waitcnt lgkmcnt(0)
	v_mfma_f32_32x32x16_bf16 v[32:47], v[184:187], v[104:107], v[32:47]
	ds_read_b64_tr_b16 v[184:185], v103 offset:4096
	ds_read_b64_tr_b16 v[186:187], v103 offset:6144
	s_waitcnt lgkmcnt(0)
	v_mfma_f32_32x32x16_bf16 v[32:47], v[184:187], v[180:183], v[32:47]
	ds_read_b64_tr_b16 v[184:185], v103 offset:8192
	ds_read_b64_tr_b16 v[186:187], v103 offset:10240
	s_waitcnt lgkmcnt(0)
	v_mfma_f32_32x32x16_bf16 v[32:47], v[184:187], v[108:111], v[32:47]
	ds_read_b64_tr_b16 v[184:185], v103 offset:12288
	ds_read_b64_tr_b16 v[186:187], v103 offset:14336
	v_xor_b32_e32 v103, 0xc0, v179
	s_waitcnt lgkmcnt(0)
	v_mfma_f32_32x32x16_bf16 v[32:47], v[184:187], v[98:101], v[32:47]
	ds_read_b64_tr_b16 v[184:185], v103 offset:0
	ds_read_b64_tr_b16 v[186:187], v103 offset:2048
	s_waitcnt lgkmcnt(0)
	v_mfma_f32_32x32x16_bf16 v[16:31], v[184:187], v[104:107], v[16:31]
	ds_read_b64_tr_b16 v[104:105], v103 offset:4096
	ds_read_b64_tr_b16 v[106:107], v103 offset:6144
	s_waitcnt lgkmcnt(0)
	v_mfma_f32_32x32x16_bf16 v[16:31], v[104:107], v[180:183], v[16:31]
	ds_read_b64_tr_b16 v[104:105], v103 offset:8192
	ds_read_b64_tr_b16 v[106:107], v103 offset:10240
	s_waitcnt lgkmcnt(0)
	v_mfma_f32_32x32x16_bf16 v[16:31], v[104:107], v[108:111], v[16:31]
	ds_read_b64_tr_b16 v[104:105], v103 offset:12288
	ds_read_b64_tr_b16 v[106:107], v103 offset:14336
	s_waitcnt lgkmcnt(0)
	v_mfma_f32_32x32x16_bf16 v[16:31], v[104:107], v[98:101], v[16:31]
	s_cbranch_scc1 .LBB0_64
	s_xor_b32 s16, s16, 1
	s_mul_i32 s16, s16, 0x8c00
	s_add_i32 s19, s16, 0x100
	s_and_saveexec_b64 s[16:17], s[8:9]
	s_cbranch_execz .LBB0_61
	v_add3_u32 v98, s19, v161, v168
	s_waitcnt vmcnt(2)
	ds_write_b128 v98, v[144:147]

.LBB0_63:
	s_or_b64 exec, exec, s[16:17]
	v_add3_u32 v98, s19, v171, v172
	s_waitcnt vmcnt(1)
	ds_write_b128 v98, v[152:155] offset:17408
	s_waitcnt vmcnt(0)
	ds_write_b128 v98, v[156:159] offset:25600

; __global__ void __launch_bounds__(512, 2) mega(Params p) {
;     ...
;                 QUEUE_BEGIN(512 + 256)
;                     if (item >= 256 && item < 512) {
;                         bf16_t* P = (bf16_t*)(R1 + R_P);
;                         const int qt = 15 - ((item - 256) >> 4), bl = (item >> 3) & 1, h = item & 7;
;                         AttnArgs a; a.Q = P + C_SBQ + h * 64; a.ldq = NINP; a.K = P + C_SBK + h * 64; a.ldk = NINP; a.K2 = nullptr; a.ldk2 = 0;
;                         a.V = P + C_SBV + h * 64; a.ldv = NINP; a.O = (bf16_t*)(R1 + R_OA) + h * 64; a.ldo = 512; a.lse = nullptr; a.ldl = 0;
;                         a.q0 = qt * 256; a.tstride = 1; a.toff = bl * SEQ; a.nk = 0; a.c2 = 0.125f * LOG2E; a.biasg = nullptr;
;                         attn_unit<2>(lds, a);
;                     } else if (item < 256) {
;                         const int qt = 15 - (item >> 4), bl = (item >> 3) & 1, h = item & 7;
;                         bf16_t* kvm = (bf16_t*)(R1 + R_KVM);
;                         AttnArgs a; a.Q = (bf16_t*)(R1 + R_QM) + h * 96; a.ldq = 768; a.K = kvm + h * 128; a.ldk = 1024; a.K2 = (bf16_t*)(R1 + R_P) + C_KR; a.ldk2 = NINP;
;                         a.V = kvm + h * 128 + 64; a.ldv = 1024; a.O = (bf16_t*)(R1 + R_OA) + (size_t)TC * 512 + h * 64; a.ldo = 512; a.lse = nullptr; a.ldl = 0;
;                         a.q0 = qt * 256; a.tstride = 1; a.toff = bl * SEQ; a.nk = 0; a.c2 = 0.10206207261596577f * LOG2E; a.biasg = nullptr;
;                         attn_unit<1>(lds, a);
;                     } else {
;                         const int t0 = (item - 512) * 32;
;                         bf16_t* oc = (bf16_t*)(R1 + R_OA) + (size_t)2 * TC * 512;
;                         const bf16_t* og = (const bf16_t*)(R1 + R_OG);
;                         const float* lse = (const float*)(R1 + R_LSE);
; #pragma unroll
;                         for (int ps = 0; ps < 4; ++ps) {
;                             const int tok = t0 + ps * 8 + (tid >> 6), c8 = (tid & 63) * 8, h = c8 >> 6;
;                             const float l0 = lse[(size_t)tok * 8 + h], l1 = lse[(size_t)(TC + tok) * 8 + h], l2 = lse[(size_t)(2 * TC + tok) * 8 + h];
;                             const float mx = fmaxf(l0, fmaxf(l1, l2));
;                             float w0 = ex2(l0 - mx), w1 = ex2(l1 - mx), w2 = ex2(l2 - mx);
.LBB0_118:
	s_or_b64 exec, exec, s[6:7]
	s_mov_b32 s0, 0x20000
	s_addk_i32 s0, 0x100
	v_mov_b32_e32 v0, s0
	s_waitcnt lgkmcnt(0)
	s_barrier
	ds_read_b32 v0, v0
	s_movk_i32 s0, 0x31f
	s_mov_b64 s[6:7], -1
	s_waitcnt lgkmcnt(0)
	v_cmp_lt_i32_e32 vcc, s0, v0
	v_readfirstlane_b32 s18, v0
	s_cbranch_vccnz .LBB0_113
	s_cmpk_lt_i32 s18, 0x120
	s_cbranch_scc1 .LBB0_122
	s_addk_i32 s18, 0xffe0
	s_and_b32 s0, s18, 0xffffff00
	s_cmpk_lg_i32 s0, 0x100
	s_cbranch_scc0 .LBB0_188
	s_cmpk_gt_i32 s18, 0xff
	s_cbranch_scc0 .LBB0_122
	s_lshl_b32 s0, s18, 5
	v_add_u32_e32 v2, s0, v197
	v_ashrrev_i32_e32 v3, 31, v2
	v_lshlrev_b64 v[4:5], 5, v[2:3]
	v_add_u32_e32 v8, 0x2000, v2
	v_lshl_add_u64 v[4:5], v[136:137], 0, v[4:5]
	v_ashrrev_i32_e32 v9, 31, v8
	global_load_dword v0, v[4:5], off
	v_lshlrev_b64 v[4:5], 5, v[8:9]
	v_add_u32_e32 v12, s0, v196
	v_lshl_add_u64 v[4:5], v[136:137], 0, v[4:5]
	v_ashrrev_i32_e32 v13, 31, v12
	global_load_dword v6, v[4:5], off
	v_lshlrev_b64 v[4:5], 5, v[12:13]
	v_lshl_add_u64 v[4:5], v[136:137], 0, v[4:5]
	global_load_dword v4, v[4:5], off
	v_lshlrev_b64 v[12:13], 10, v[12:13]
	v_lshl_add_u64 v[12:13], v[138:139], 0, v[12:13]
	global_load_dwordx4 v[12:15], v[12:13], off
	v_lshlrev_b64 v[20:21], 10, v[2:3]
	v_lshlrev_b64 v[8:9], 10, v[8:9]
	v_lshl_add_u64 v[8:9], v[138:139], 0, v[8:9]
	s_mov_b64 s[6:7], 0
	s_waitcnt vmcnt(0)
	v_max3_f32 v5, v0, v6, v4
	v_sub_f32_e32 v0, v0, v5
	v_exp_f32_e32 v17, v0
	v_sub_f32_e32 v0, v6, v5
	v_exp_f32_e32 v16, v0
	v_sub_f32_e32 v0, v4, v5
	v_exp_f32_e32 v4, v0
	s_waitcnt vmcnt(0)
	v_lshlrev_b32_e32 v26, 16, v12
	v_add_f32_e32 v0, v17, v16
	v_and_b32_e32 v27, 0xffff0000, v12
	v_add_f32_e32 v0, v4, v0
	v_div_scale_f32 v5, s[0:1], v0, v0, 1.0
	v_rcp_f32_e32 v6, v5
	v_lshlrev_b32_e32 v12, 16, v13
	v_and_b32_e32 v13, 0xffff0000, v13
	v_fma_f32 v7, -v5, v6, 1.0
	v_fmac_f32_e32 v6, v7, v6
	v_div_scale_f32 v7, vcc, 1.0, v0, 1.0
	v_mul_f32_e32 v10, v7, v6
	v_fma_f32 v11, -v5, v10, v7
	v_fmac_f32_e32 v10, v11, v6
	v_fma_f32 v5, -v5, v10, v7
	v_div_fmas_f32 v5, v5, v6, v10
	v_div_fixup_f32 v0, v5, v0, 1.0
	v_mul_f32_e32 v18, v4, v0
	v_lshl_add_u64 v[4:5], v[138:139], 0, v[20:21]
	global_load_dwordx4 v[4:7], v[4:5], off
	v_pk_mul_f32 v[16:17], v[16:17], v[0:1] op_sel_hi:[1,0]
	global_load_dwordx4 v[8:11], v[8:9], off
	s_waitcnt vmcnt(1)
	v_lshlrev_b32_e32 v24, 16, v4
	v_and_b32_e32 v23, 0xffff0000, v4
	s_waitcnt vmcnt(0)
	v_and_b32_e32 v25, 0xffff0000, v8
	v_lshlrev_b32_e32 v22, 16, v8
	v_pk_mul_f32 v[24:25], v[16:17], v[24:25] op_sel:[1,0] op_sel_hi:[0,1]
	v_pk_fma_f32 v[22:23], v[16:17], v[22:23], v[24:25]
	v_lshlrev_b32_e32 v8, 16, v5
	v_pk_fma_f32 v[22:23], v[18:19], v[26:27], v[22:23] op_sel_hi:[0,1,1]
	v_cvt_pk_bf16_f32 v4, v22, v23
	v_lshlrev_b32_e32 v22, 16, v9
	v_and_b32_e32 v9, 0xffff0000, v9
	v_and_b32_e32 v23, 0xffff0000, v5
	v_pk_mul_f32 v[8:9], v[16:17], v[8:9] op_sel:[1,0] op_sel_hi:[0,1]
	v_pk_fma_f32 v[8:9], v[16:17], v[22:23], v[8:9]
	v_lshlrev_b32_e32 v22, 16, v14
	v_pk_fma_f32 v[8:9], v[18:19], v[12:13], v[8:9] op_sel_hi:[0,1,1]
	v_lshlrev_b32_e32 v12, 16, v6
	v_and_b32_e32 v13, 0xffff0000, v10
	v_cvt_pk_bf16_f32 v5, v8, v9
	v_lshlrev_b32_e32 v8, 16, v10
	v_and_b32_e32 v9, 0xffff0000, v6
	v_pk_mul_f32 v[12:13], v[16:17], v[12:13] op_sel:[1,0] op_sel_hi:[0,1]
	v_and_b32_e32 v23, 0xffff0000, v14
	v_pk_fma_f32 v[8:9], v[16:17], v[8:9], v[12:13]
	v_lshlrev_b32_e32 v10, 16, v7
	v_pk_fma_f32 v[8:9], v[18:19], v[22:23], v[8:9] op_sel_hi:[0,1,1]
	v_cvt_pk_bf16_f32 v6, v8, v9
	v_lshlrev_b32_e32 v8, 16, v11
	v_and_b32_e32 v11, 0xffff0000, v11
	v_and_b32_e32 v9, 0xffff0000, v7
	v_pk_mul_f32 v[10:11], v[16:17], v[10:11] op_sel:[1,0] op_sel_hi:[0,1]
	v_pk_fma_f32 v[8:9], v[16:17], v[8:9], v[10:11]
	v_lshlrev_b32_e32 v10, 16, v15
	v_and_b32_e32 v11, 0xffff0000, v15
	v_pk_fma_f32 v[8:9], v[18:19], v[10:11], v[8:9] op_sel_hi:[0,1,1]
	v_cvt_pk_bf16_f32 v7, v8, v9
	v_lshl_add_u64 v[8:9], v[140:141], 0, v[20:21]
	global_store_dwordx4 v[8:9], v[4:7], off
	v_add_u32_e32 v8, 0x2008, v2
	v_ashrrev_i32_e32 v9, 31, v8
	v_add_u32_e32 v4, 8, v2
	v_ashrrev_i32_e32 v5, 31, v4
	v_lshlrev_b64 v[6:7], 5, v[4:5]
	v_lshl_add_u64 v[6:7], v[136:137], 0, v[6:7]
	global_load_dword v0, v[6:7], off
	v_lshlrev_b64 v[6:7], 5, v[8:9]
	v_add_u32_e32 v12, 0x4008, v2
	v_lshl_add_u64 v[6:7], v[136:137], 0, v[6:7]
	v_ashrrev_i32_e32 v13, 31, v12
	global_load_dword v3, v[6:7], off
	v_lshlrev_b64 v[6:7], 5, v[12:13]
	v_lshl_add_u64 v[6:7], v[136:137], 0, v[6:7]
	global_load_dword v6, v[6:7], off
	v_lshlrev_b64 v[20:21], 10, v[4:5]
	v_lshlrev_b64 v[8:9], 10, v[8:9]
	v_lshl_add_u64 v[4:5], v[138:139], 0, v[20:21]
	v_lshl_add_u64 v[8:9], v[138:139], 0, v[8:9]
	v_lshlrev_b64 v[12:13], 10, v[12:13]
	v_lshl_add_u64 v[12:13], v[138:139], 0, v[12:13]
	s_waitcnt vmcnt(0)
	v_max3_f32 v7, v0, v3, v6
	v_sub_f32_e32 v0, v0, v7
	v_exp_f32_e32 v17, v0
	v_sub_f32_e32 v0, v3, v7
	v_exp_f32_e32 v16, v0
	v_sub_f32_e32 v0, v6, v7
	v_exp_f32_e32 v3, v0
	v_add_f32_e32 v0, v17, v16
	v_add_f32_e32 v0, v3, v0
	v_div_scale_f32 v6, s[0:1], v0, v0, 1.0
	v_rcp_f32_e32 v7, v6
	s_nop 0
	v_fma_f32 v10, -v6, v7, 1.0
	v_fmac_f32_e32 v7, v10, v7
	v_div_scale_f32 v10, vcc, 1.0, v0, 1.0
	v_mul_f32_e32 v11, v10, v7
	v_fma_f32 v14, -v6, v11, v10
	v_fmac_f32_e32 v11, v14, v7
	v_fma_f32 v6, -v6, v11, v10
	v_div_fmas_f32 v6, v6, v7, v11
	v_div_fixup_f32 v0, v6, v0, 1.0
	global_load_dwordx4 v[4:7], v[4:5], off
	v_pk_mul_f32 v[16:17], v[16:17], v[0:1] op_sel_hi:[1,0]
	global_load_dwordx4 v[8:11], v[8:9], off
	v_mul_f32_e32 v18, v3, v0
	global_load_dwordx4 v[12:15], v[12:13], off
	s_waitcnt vmcnt(2)
	v_lshlrev_b32_e32 v24, 16, v4
	v_and_b32_e32 v23, 0xffff0000, v4
	s_waitcnt vmcnt(1)
; DI unsigned pk2(float lo, float hi) { f32x2_t v = {lo, hi}; bf16x2_t b = __builtin_convertvector(v, bf16x2_t); return __builtin_bit_cast(unsigned, b); }
; DI float bflo(unsigned u) { return __uint_as_float(u << 16); }
; DI float bfhi(unsigned u) { return __uint_as_float(u & 0xffff0000u); }
; DI float ex2(float x) { return __builtin_amdgcn_exp2f(x); }
; __global__ void __launch_bounds__(512, 2) mega(Params p) {
;     ...
;                         for (int ps = 0; ps < 4; ++ps) {
;                             const int tok = t0 + ps * 8 + (tid >> 6), c8 = (tid & 63) * 8, h = c8 >> 6;
;                             const float l0 = lse[(size_t)tok * 8 + h], l1 = lse[(size_t)(TC + tok) * 8 + h], l2 = lse[(size_t)(2 * TC + tok) * 8 + h];
;                             const float mx = fmaxf(l0, fmaxf(l1, l2));
;                             float w0 = ex2(l0 - mx), w1 = ex2(l1 - mx), w2 = ex2(l2 - mx);
;                             const float is = 1.0f / (w0 + w1 + w2); w0 *= is; w1 *= is; w2 *= is;
;                             const u32x4 a0 = *(const u32x4*)(og + (size_t)tok * 512 + c8), a1 = *(const u32x4*)(og + (size_t)(TC + tok) * 512 + c8), a2 = *(const u32x4*)(og + (size_t)(2 * TC + tok) * 512 + c8);
;                             u32x4 w;
;                             w.x = pk2(w0 * bflo(a0.x) + w1 * bflo(a1.x) + w2 * bflo(a2.x), w0 * bfhi(a0.x) + w1 * bfhi(a1.x) + w2 * bfhi(a2.x));
;                             w.y = pk2(w0 * bflo(a0.y) + w1 * bflo(a1.y) + w2 * bflo(a2.y), w0 * bfhi(a0.y) + w1 * bfhi(a1.y) + w2 * bfhi(a2.y));
;                             w.z = pk2(w0 * bflo(a0.z) + w1 * bflo(a1.z) + w2 * bflo(a2.z), w0 * bfhi(a0.z) + w1 * bfhi(a1.z) + w2 * bfhi(a2.z));
;                             w.w = pk2(w0 * bflo(a0.w) + w1 * bflo(a1.w) + w2 * bflo(a2.w), w0 * bfhi(a0.w) + w1 * bfhi(a1.w) + w2 * bfhi(a2.w));
;                             *(u32x4*)(oc + (size_t)tok * 512 + c8) = w;
;                         }
	v_and_b32_e32 v25, 0xffff0000, v8
	v_lshlrev_b32_e32 v22, 16, v8
	v_pk_mul_f32 v[24:25], v[16:17], v[24:25] op_sel:[1,0] op_sel_hi:[0,1]
	s_waitcnt vmcnt(0)
	v_lshlrev_b32_e32 v26, 16, v12
	v_and_b32_e32 v27, 0xffff0000, v12
	v_pk_fma_f32 v[22:23], v[16:17], v[22:23], v[24:25]
	v_lshlrev_b32_e32 v8, 16, v5
	v_pk_fma_f32 v[22:23], v[18:19], v[26:27], v[22:23] op_sel_hi:[0,1,1]
	v_cvt_pk_bf16_f32 v4, v22, v23
	v_lshlrev_b32_e32 v22, 16, v9
	v_and_b32_e32 v9, 0xffff0000, v9
	v_and_b32_e32 v23, 0xffff0000, v5
	v_pk_mul_f32 v[8:9], v[16:17], v[8:9] op_sel:[1,0] op_sel_hi:[0,1]
	v_lshlrev_b32_e32 v12, 16, v13
	v_and_b32_e32 v13, 0xffff0000, v13
	v_pk_fma_f32 v[8:9], v[16:17], v[22:23], v[8:9]
	v_lshlrev_b32_e32 v22, 16, v14
	v_pk_fma_f32 v[8:9], v[18:19], v[12:13], v[8:9] op_sel_hi:[0,1,1]
	v_lshlrev_b32_e32 v12, 16, v6
	v_and_b32_e32 v13, 0xffff0000, v10
	v_cvt_pk_bf16_f32 v5, v8, v9
	v_lshlrev_b32_e32 v8, 16, v10
	v_and_b32_e32 v9, 0xffff0000, v6
	v_pk_mul_f32 v[12:13], v[16:17], v[12:13] op_sel:[1,0] op_sel_hi:[0,1]
	v_and_b32_e32 v23, 0xffff0000, v14
	v_pk_fma_f32 v[8:9], v[16:17], v[8:9], v[12:13]
	v_lshlrev_b32_e32 v10, 16, v7
	v_pk_fma_f32 v[8:9], v[18:19], v[22:23], v[8:9] op_sel_hi:[0,1,1]
	v_cvt_pk_bf16_f32 v6, v8, v9
	v_lshlrev_b32_e32 v8, 16, v11
	v_and_b32_e32 v11, 0xffff0000, v11
	v_and_b32_e32 v9, 0xffff0000, v7
	v_pk_mul_f32 v[10:11], v[16:17], v[10:11] op_sel:[1,0] op_sel_hi:[0,1]
	v_pk_fma_f32 v[8:9], v[16:17], v[8:9], v[10:11]
	v_lshlrev_b32_e32 v10, 16, v15
	v_and_b32_e32 v11, 0xffff0000, v15
	v_pk_fma_f32 v[8:9], v[18:19], v[10:11], v[8:9] op_sel_hi:[0,1,1]
	v_cvt_pk_bf16_f32 v7, v8, v9
	v_lshl_add_u64 v[8:9], v[140:141], 0, v[20:21]
	global_store_dwordx4 v[8:9], v[4:7], off
	v_add_u32_e32 v8, 0x2010, v2
	v_ashrrev_i32_e32 v9, 31, v8
	v_add_u32_e32 v4, 16, v2
	v_ashrrev_i32_e32 v5, 31, v4
	v_lshlrev_b64 v[6:7], 5, v[4:5]
	v_lshl_add_u64 v[6:7], v[136:137], 0, v[6:7]
	global_load_dword v0, v[6:7], off
	v_lshlrev_b64 v[6:7], 5, v[8:9]
	v_add_u32_e32 v12, 0x4010, v2
	v_lshl_add_u64 v[6:7], v[136:137], 0, v[6:7]
	v_ashrrev_i32_e32 v13, 31, v12
	global_load_dword v3, v[6:7], off
	v_lshlrev_b64 v[6:7], 5, v[12:13]
	v_lshl_add_u64 v[6:7], v[136:137], 0, v[6:7]
	global_load_dword v6, v[6:7], off
	v_lshlrev_b64 v[20:21], 10, v[4:5]
	v_lshlrev_b64 v[8:9], 10, v[8:9]
	v_lshl_add_u64 v[4:5], v[138:139], 0, v[20:21]
	v_lshl_add_u64 v[8:9], v[138:139], 0, v[8:9]
	v_lshlrev_b64 v[12:13], 10, v[12:13]
	v_lshl_add_u64 v[12:13], v[138:139], 0, v[12:13]
	s_waitcnt vmcnt(0)
	v_max3_f32 v7, v0, v3, v6
	v_sub_f32_e32 v0, v0, v7
	v_exp_f32_e32 v17, v0
	v_sub_f32_e32 v0, v3, v7
	v_exp_f32_e32 v16, v0
	v_sub_f32_e32 v0, v6, v7
	v_exp_f32_e32 v3, v0
	v_add_f32_e32 v0, v17, v16
	v_add_f32_e32 v0, v3, v0
	v_div_scale_f32 v6, s[0:1], v0, v0, 1.0
	v_rcp_f32_e32 v7, v6
	s_nop 0
	v_fma_f32 v10, -v6, v7, 1.0
	v_fmac_f32_e32 v7, v10, v7
	v_div_scale_f32 v10, vcc, 1.0, v0, 1.0
	v_mul_f32_e32 v11, v10, v7
	v_fma_f32 v14, -v6, v11, v10
	v_fmac_f32_e32 v11, v14, v7
	v_fma_f32 v6, -v6, v11, v10
	v_div_fmas_f32 v6, v6, v7, v11
	v_div_fixup_f32 v0, v6, v0, 1.0
	global_load_dwordx4 v[4:7], v[4:5], off
	v_pk_mul_f32 v[16:17], v[16:17], v[0:1] op_sel_hi:[1,0]
	global_load_dwordx4 v[8:11], v[8:9], off
	v_mul_f32_e32 v18, v3, v0
	global_load_dwordx4 v[12:15], v[12:13], off
	s_waitcnt vmcnt(2)
	v_lshlrev_b32_e32 v24, 16, v4
	v_and_b32_e32 v23, 0xffff0000, v4
	s_waitcnt vmcnt(1)
	v_and_b32_e32 v25, 0xffff0000, v8
	v_lshlrev_b32_e32 v22, 16, v8
	v_pk_mul_f32 v[24:25], v[16:17], v[24:25] op_sel:[1,0] op_sel_hi:[0,1]
	s_waitcnt vmcnt(0)
	v_lshlrev_b32_e32 v26, 16, v12
	v_and_b32_e32 v27, 0xffff0000, v12
	v_pk_fma_f32 v[22:23], v[16:17], v[22:23], v[24:25]
	v_lshlrev_b32_e32 v8, 16, v5
	v_pk_fma_f32 v[22:23], v[18:19], v[26:27], v[22:23] op_sel_hi:[0,1,1]
	v_cvt_pk_bf16_f32 v4, v22, v23
	v_lshlrev_b32_e32 v22, 16, v9
	v_and_b32_e32 v9, 0xffff0000, v9
	v_and_b32_e32 v23, 0xffff0000, v5
	v_pk_mul_f32 v[8:9], v[16:17], v[8:9] op_sel:[1,0] op_sel_hi:[0,1]
	v_lshlrev_b32_e32 v12, 16, v13
	v_and_b32_e32 v13, 0xffff0000, v13
	v_pk_fma_f32 v[8:9], v[16:17], v[22:23], v[8:9]
	v_lshlrev_b32_e32 v22, 16, v14
	v_pk_fma_f32 v[8:9], v[18:19], v[12:13], v[8:9] op_sel_hi:[0,1,1]
	v_lshlrev_b32_e32 v12, 16, v6
	v_and_b32_e32 v13, 0xffff0000, v10
	v_cvt_pk_bf16_f32 v5, v8, v9
	v_lshlrev_b32_e32 v8, 16, v10
	v_and_b32_e32 v9, 0xffff0000, v6
	v_pk_mul_f32 v[12:13], v[16:17], v[12:13] op_sel:[1,0] op_sel_hi:[0,1]
	v_and_b32_e32 v23, 0xffff0000, v14
	v_pk_fma_f32 v[8:9], v[16:17], v[8:9], v[12:13]
	v_lshlrev_b32_e32 v10, 16, v7
	v_pk_fma_f32 v[8:9], v[18:19], v[22:23], v[8:9] op_sel_hi:[0,1,1]
	v_cvt_pk_bf16_f32 v6, v8, v9
	v_lshlrev_b32_e32 v8, 16, v11
	v_and_b32_e32 v11, 0xffff0000, v11
	v_and_b32_e32 v9, 0xffff0000, v7
	v_pk_mul_f32 v[10:11], v[16:17], v[10:11] op_sel:[1,0] op_sel_hi:[0,1]
	v_pk_fma_f32 v[8:9], v[16:17], v[8:9], v[10:11]
	v_lshlrev_b32_e32 v10, 16, v15
	v_and_b32_e32 v11, 0xffff0000, v15
	v_pk_fma_f32 v[8:9], v[18:19], v[10:11], v[8:9] op_sel_hi:[0,1,1]
	v_cvt_pk_bf16_f32 v7, v8, v9
	v_lshl_add_u64 v[8:9], v[140:141], 0, v[20:21]
	global_store_dwordx4 v[8:9], v[4:7], off
	v_add_u32_e32 v12, 0x4018, v2
	v_ashrrev_i32_e32 v13, 31, v12
	v_add_u32_e32 v4, 24, v2
	v_ashrrev_i32_e32 v5, 31, v4
	v_lshlrev_b64 v[6:7], 5, v[4:5]
	v_add_u32_e32 v8, 0x2018, v2
	v_lshlrev_b64 v[2:3], 5, v[12:13]
	v_lshlrev_b64 v[12:13], 10, v[12:13]
	v_lshl_add_u64 v[6:7], v[136:137], 0, v[6:7]
	v_ashrrev_i32_e32 v9, 31, v8
	v_lshl_add_u64 v[2:3], v[136:137], 0, v[2:3]
	v_lshl_add_u64 v[12:13], v[138:139], 0, v[12:13]
	global_load_dword v0, v[6:7], off
	s_nop 0
	global_load_dwordx4 v[12:15], v[12:13], off
	s_waitcnt vmcnt(0)
; __global__ void __launch_bounds__(512, 2) mega(Params p) {
;     ...
;                         const int qt = 15 - ((item - 256) >> 4), bl = (item >> 3) & 1, h = item & 7;
;                         AttnArgs a; a.Q = P + C_SBQ + h * 64; a.ldq = NINP; a.K = P + C_SBK + h * 64; a.ldk = NINP; a.K2 = nullptr; a.ldk2 = 0;
;                         a.V = P + C_SBV + h * 64; a.ldv = NINP; a.O = (bf16_t*)(R1 + R_OA) + h * 64; a.ldo = 512; a.lse = nullptr; a.ldl = 0;
;                         a.q0 = qt * 256; a.tstride = 1; a.toff = bl * SEQ; a.nk = 0; a.c2 = 0.125f * LOG2E; a.biasg = nullptr;
;                         attn_unit<2>(lds, a);
;                     } else if (item < 256) {
;                         const int qt = 15 - (item >> 4), bl = (item >> 3) & 1, h = item & 7;
;                         bf16_t* kvm = (bf16_t*)(R1 + R_KVM);
;     ...
;                         for (int ps = 0; ps < 4; ++ps) {
;                             const int tok = t0 + ps * 8 + (tid >> 6), c8 = (tid & 63) * 8, h = c8 >> 6;
;                             const float l0 = lse[(size_t)tok * 8 + h], l1 = lse[(size_t)(TC + tok) * 8 + h], l2 = lse[(size_t)(2 * TC + tok) * 8 + h];
;                             const float mx = fmaxf(l0, fmaxf(l1, l2));
;                             float w0 = ex2(l0 - mx), w1 = ex2(l1 - mx), w2 = ex2(l2 - mx);
;                             const float is = 1.0f / (w0 + w1 + w2); w0 *= is; w1 *= is; w2 *= is;
;                             const u32x4 a0 = *(const u32x4*)(og + (size_t)tok * 512 + c8), a1 = *(const u32x4*)(og + (size_t)(TC + tok) * 512 + c8), a2 = *(const u32x4*)(og + (size_t)(2 * TC + tok) * 512 + c8);
;                             u32x4 w;
;                             w.x = pk2(w0 * bflo(a0.x) + w1 * bflo(a1.x) + w2 * bflo(a2.x), w0 * bfhi(a0.x) + w1 * bfhi(a1.x) + w2 * bfhi(a2.x));
;                             w.y = pk2(w0 * bflo(a0.y) + w1 * bflo(a1.y) + w2 * bflo(a2.y), w0 * bfhi(a0.y) + w1 * bfhi(a1.y) + w2 * bfhi(a2.y));
;                             w.z = pk2(w0 * bflo(a0.z) + w1 * bflo(a1.z) + w2 * bflo(a2.z), w0 * bfhi(a0.z) + w1 * bfhi(a1.z) + w2 * bfhi(a2.z));
;                             w.w = pk2(w0 * bflo(a0.w) + w1 * bflo(a1.w) + w2 * bflo(a2.w), w0 * bfhi(a0.w) + w1 * bfhi(a1.w) + w2 * bfhi(a2.w));
;                             *(u32x4*)(oc + (size_t)tok * 512 + c8) = w;
;                         }
	v_lshlrev_b32_e32 v24, 16, v12
	global_load_dword v2, v[2:3], off
	v_lshlrev_b64 v[6:7], 5, v[8:9]
	v_lshl_add_u64 v[6:7], v[136:137], 0, v[6:7]
	global_load_dword v6, v[6:7], off
	v_lshlrev_b64 v[8:9], 10, v[8:9]
	v_lshl_add_u64 v[8:9], v[138:139], 0, v[8:9]
	v_and_b32_e32 v25, 0xffff0000, v12
	v_lshlrev_b32_e32 v12, 16, v13
	v_and_b32_e32 v13, 0xffff0000, v13
	s_waitcnt vmcnt(0)
	v_max3_f32 v3, v0, v6, v2
	v_sub_f32_e32 v0, v0, v3
	v_exp_f32_e32 v17, v0
	v_sub_f32_e32 v0, v6, v3
	v_exp_f32_e32 v16, v0
	v_sub_f32_e32 v0, v2, v3
	v_exp_f32_e32 v2, v0
	v_add_f32_e32 v0, v17, v16
	v_add_f32_e32 v0, v2, v0
	v_div_scale_f32 v3, s[0:1], v0, v0, 1.0
	v_rcp_f32_e32 v6, v3
	s_nop 0
	v_fma_f32 v7, -v3, v6, 1.0
	v_fmac_f32_e32 v6, v7, v6
	v_div_scale_f32 v7, vcc, 1.0, v0, 1.0
	v_mul_f32_e32 v10, v7, v6
	v_fma_f32 v11, -v3, v10, v7
	v_fmac_f32_e32 v10, v11, v6
	v_fma_f32 v3, -v3, v10, v7
	v_div_fmas_f32 v3, v3, v6, v10
	v_div_fixup_f32 v0, v3, v0, 1.0
	v_lshlrev_b64 v[6:7], 10, v[4:5]
	v_mul_f32_e32 v18, v2, v0
	v_lshl_add_u64 v[2:3], v[138:139], 0, v[6:7]
	global_load_dwordx4 v[2:5], v[2:3], off
	v_pk_mul_f32 v[16:17], v[16:17], v[0:1] op_sel_hi:[1,0]
	global_load_dwordx4 v[8:11], v[8:9], off
	v_lshl_add_u64 v[6:7], v[140:141], 0, v[6:7]
	s_waitcnt vmcnt(1)
	v_lshlrev_b32_e32 v22, 16, v2
	v_and_b32_e32 v21, 0xffff0000, v2
	s_waitcnt vmcnt(0)
	v_and_b32_e32 v23, 0xffff0000, v8
	v_lshlrev_b32_e32 v20, 16, v8
	v_pk_mul_f32 v[22:23], v[16:17], v[22:23] op_sel:[1,0] op_sel_hi:[0,1]
	v_pk_fma_f32 v[20:21], v[16:17], v[20:21], v[22:23]
	v_lshlrev_b32_e32 v8, 16, v3
	v_pk_fma_f32 v[20:21], v[18:19], v[24:25], v[20:21] op_sel_hi:[0,1,1]
	v_cvt_pk_bf16_f32 v2, v20, v21
	v_lshlrev_b32_e32 v20, 16, v9
	v_and_b32_e32 v9, 0xffff0000, v9
	v_and_b32_e32 v21, 0xffff0000, v3
	v_pk_mul_f32 v[8:9], v[16:17], v[8:9] op_sel:[1,0] op_sel_hi:[0,1]
	v_pk_fma_f32 v[8:9], v[16:17], v[20:21], v[8:9]
	v_lshlrev_b32_e32 v20, 16, v14
	v_pk_fma_f32 v[8:9], v[18:19], v[12:13], v[8:9] op_sel_hi:[0,1,1]
	v_lshlrev_b32_e32 v12, 16, v4
	v_and_b32_e32 v13, 0xffff0000, v10
	v_cvt_pk_bf16_f32 v3, v8, v9
	v_lshlrev_b32_e32 v8, 16, v10
	v_and_b32_e32 v9, 0xffff0000, v4
	v_pk_mul_f32 v[12:13], v[16:17], v[12:13] op_sel:[1,0] op_sel_hi:[0,1]
	v_and_b32_e32 v21, 0xffff0000, v14
	v_pk_fma_f32 v[8:9], v[16:17], v[8:9], v[12:13]
	v_lshlrev_b32_e32 v10, 16, v5
	v_pk_fma_f32 v[8:9], v[18:19], v[20:21], v[8:9] op_sel_hi:[0,1,1]
	v_cvt_pk_bf16_f32 v4, v8, v9
	v_lshlrev_b32_e32 v8, 16, v11
	v_and_b32_e32 v11, 0xffff0000, v11
	v_and_b32_e32 v9, 0xffff0000, v5
	v_pk_mul_f32 v[10:11], v[16:17], v[10:11] op_sel:[1,0] op_sel_hi:[0,1]
	v_pk_fma_f32 v[8:9], v[16:17], v[8:9], v[10:11]
	v_lshlrev_b32_e32 v10, 16, v15
	v_and_b32_e32 v11, 0xffff0000, v15
	v_pk_fma_f32 v[8:9], v[18:19], v[10:11], v[8:9] op_sel_hi:[0,1,1]
	v_cvt_pk_bf16_f32 v5, v8, v9
	global_store_dwordx4 v[6:7], v[2:5], off
.LBB0_122:
	s_andn2_b64 vcc, exec, s[6:7]
	s_cbranch_vccnz .LBB0_187
	s_and_b32 s1, s18, 7
	s_mul_i32 s0, s1, 0xc0
	v_readlane_b32 s4, v254, 57
	v_readlane_b32 s5, v254, 58
	s_add_u32 s8, s4, s0
	s_addc_u32 s9, s5, 0
	s_lshl_b32 s0, s1, 8
	v_readlane_b32 s4, v254, 55
	v_readlane_b32 s5, v254, 56
	s_add_u32 s6, s4, s0
	s_addc_u32 s7, s5, 0
	s_lshl_b32 s5, s18, 9
	v_mov_b32_e32 v12, v202
	s_lshl_b32 s0, s18, 3
	s_and_b32 s66, s5, 0x1000
	s_and_b32 s0, s0, 0xffffff80
	s_cmpk_lt_i32 s18, 0x40
	s_cselect_b32 s32, 1, 0
	s_cbranch_scc1 .Lq_half
	s_sub_i32 s0, s18, 0x40
	s_lshl_b32 s0, s0, 4
	s_and_b32 s0, s0, 0xffffff00
	s_addk_i32 s0, 0x280
.Lq_half:
	v_readfirstlane_b32 s5, v12
	s_ashr_i32 s5, s5, 1
	s_sub_i32 s4, 0xf80, s0
	s_and_b32 s19, s5, 0xffffffe0
	s_lshr_b32 s98, s19, 7
	s_and_b32 s98, s98, s32
	v_and_b32_e32 v13, 31, v12
	s_add_i32 s19, s19, s4
	s_waitcnt vmcnt(0)
	v_or_b32_e32 v134, s19, v13
	v_ashrrev_i32_e32 v135, 31, v134
	v_lshl_add_u64 v[132:133], v[134:135], 0, s[66:67]
	v_mov_b64_e32 v[2:3], s[8:9]
	v_bfe_u32 v48, v12, 5, 1
	v_mad_u64_u32 v[2:3], s[8:9], v132, s81, v[2:3]
	v_mad_i32_i24 v3, v133, s81, v3
	v_lshlrev_b32_e32 v0, 4, v48
	v_lshl_add_u64 v[2:3], v[2:3], 0, v[0:1]
	global_load_dwordx4 v[96:99], v[2:3], off
	global_load_dwordx4 v[100:103], v[2:3], off offset:32
	global_load_dwordx4 v[104:107], v[2:3], off offset:64
	global_load_dwordx4 v[108:111], v[2:3], off offset:96
	global_load_dwordx4 v[112:115], v[2:3], off offset:128
	global_load_dwordx4 v[116:119], v[2:3], off offset:160
	s_movk_i32 s5, 0x300
	v_cmp_gt_i32_e64 s[10:11], s5, v12
	s_mov_b32 s5, 0x2aaaaaab
	v_mul_hi_i32 v0, v12, s5
	v_lshrrev_b32_e32 v14, 31, v0
	v_ashrrev_i32_e32 v15, 1, v0
	s_and_saveexec_b64 s[8:9], s[10:11]
	s_cbranch_execz .LBB0_129
	v_add_u32_e32 v2, v15, v14
	v_mul_lo_u32 v0, v2, 12
	v_sub_u32_e32 v0, v12, v0
	v_ashrrev_i32_e32 v3, 31, v2
	v_lshl_add_u64 v[2:3], v[2:3], 0, s[66:67]
	v_cmp_gt_i32_e32 vcc, 8, v0
	v_lshlrev_b32_e32 v0, 3, v0
	s_and_saveexec_b64 s[12:13], vcc
	s_xor_b64 s[12:13], exec, s[12:13]
	v_lshlrev_b64 v[2:3], 11, v[2:3]
	v_lshl_add_u64 v[2:3], s[6:7], 0, v[2:3]
	v_ashrrev_i32_e32 v5, 31, v0
	v_mov_b32_e32 v4, v0
	v_lshl_add_u64 v[4:5], v[4:5], 1, v[2:3]
	s_andn2_saveexec_b64 s[12:13], s[12:13]
	s_cbranch_execz .LBB0_128
	v_readlane_b32 s14, v255, 13
	v_readlane_b32 s15, v255, 14
	s_nop 1
	v_mov_b64_e32 v[4:5], s[14:15]
	v_mad_u64_u32 v[4:5], s[14:15], v2, s86, v[4:5]
	v_mad_i32_i24 v5, v3, s86, v5
	s_movk_i32 s14, 0xff80
	v_lshl_add_u64 v[2:3], v[0:1], 1, v[4:5]
	s_mov_b32 s15, -1
	v_lshl_add_u64 v[4:5], v[2:3], 0, s[14:15]

; #define LAS __attribute__((address_space(3)))
; template <int MODE>
; DI void attn_unit(LAS unsigned char* lds, const AttnArgs a) {
;     ...
;     f32x16 o[NDB];
; #pragma unroll
;     for (int d = 0; d < NDB; ++d)
; #pragma unroll
;         for (int i = 0; i < 16; ++i) o[d][i] = 0.f;
;     float mrow = -1e30f, lrow = 0.f, carry = 1.f;
;     int ntile;
;     if (MODE == 0) ntile = a.nk / 64; else if (MODE == 1) ntile = (a.q0 + 255) / 64 + 1; else if (MODE == 2) ntile = (a.q0 + 254) / 64 + 1; else ntile = 6;
;     const int it0 = (MODE == 3 && a.q0 == 0) ? 2 : 0;
;     constexpr int NKC = (64 * (DK / 8) + 511) / 512, NVC = (64 * (DV / 8) + 511) / 512;
;     u32x4 kreg[NKC], vreg[NVC];
;     ...
;     ATT_LOAD(it0);
;     ATT_STORE(0);
;     __syncthreads();
;     if (it0 + 1 < ntile) ATT_LOAD(it0 + 1);
;     bool sb_dead = false;
;     for (int it = it0; it < ntile; ++it) {
;         const int kbase = ATT_KBASE(it), cur = (it - it0) & 1;
;         const LAS bf16_t* Kc = Ks + cur * BUFE; const LAS bf16_t* Vc = Vt + cur * BUFE;
;         bool active = true;
;         if (MODE == 1) active = kbase <= q0w + 31;
;         if (MODE == 2) active = (kbase <= q0w + 30) && !sb_dead;
.LBB0_153:
	s_mov_b64 s[8:9], -1
	s_cmpk_gt_i32 s4, 0xfec1
	v_lshlrev_b32_e32 v198, 2, v48
	s_cbranch_scc0 .LBB0_184
	v_lshlrev_b32_e32 v142, 2, v48
	v_lshl_add_u64 v[144:145], v[4:5], 1, s[6:7]
	v_lshrrev_b32_e32 v4, 1, v12
	v_and_b32_e32 v5, 12, v4
	v_bitop3_b32 v200, v142, v4, 12 bitop3:0x78
	v_or_b32_e32 v4, 32, v13
	v_or_b32_e32 v3, 8, v142
	v_lshrrev_b32_e32 v4, 1, v4
	v_or_b32_e32 v6, 16, v142
	v_or_b32_e32 v7, 24, v142
	v_or_b32_e32 v8, 32, v142
	v_or_b32_e32 v9, 40, v142
	v_or_b32_e32 v10, 48, v142
	v_or_b32_e32 v11, 56, v142
	v_bitop3_b32 v215, v4, v3, 28 bitop3:0x6c
	v_add_u32_e32 v3, v15, v14
	v_bitop3_b32 v214, v4, v142, 28 bitop3:0x6c
	v_bitop3_b32 v216, v4, v6, 28 bitop3:0x6c
	v_bitop3_b32 v217, v4, v7, 28 bitop3:0x6c
	v_bitop3_b32 v218, v4, v8, 28 bitop3:0x6c
	v_bitop3_b32 v219, v4, v9, 28 bitop3:0x6c
	v_bitop3_b32 v220, v4, v10, 28 bitop3:0x6c
	v_bitop3_b32 v221, v4, v11, 28 bitop3:0x6c
	v_mul_lo_u32 v4, v3, 12
	s_movk_i32 s8, 0x90
	v_sub_u32_e32 v4, v12, v4
	v_add_u32_e32 v6, v52, v51
	v_bitop3_b32 v201, v142, v5, 8 bitop3:0x36
	v_bitop3_b32 v205, v142, v5, 16 bitop3:0x36
	v_bitop3_b32 v208, v142, v5, 24 bitop3:0x36
	v_bitop3_b32 v209, v142, v5, 32 bitop3:0x36
	v_bitop3_b32 v210, v142, v5, 40 bitop3:0x36
	v_bitop3_b32 v211, v142, v5, 48 bitop3:0x36
	v_bitop3_b32 v212, v142, v5, 56 bitop3:0x36
	v_mad_u32_u24 v213, v13, s8, v238
	s_movk_i32 s8, 0xd0
	v_lshlrev_b32_e32 v223, 4, v4
	v_mul_lo_u32 v5, v6, 12
	v_cmp_gt_i32_e64 s[14:15], 8, v4
	v_lshlrev_b32_e32 v4, 3, v4
	v_mul_lo_u32 v222, v3, s8
	v_sub_u32_e32 v7, v50, v5
	v_mul_lo_u32 v224, v6, s8
	v_ashrrev_i32_e32 v5, 31, v4
	v_readlane_b32 s8, v255, 13
	v_lshl_add_u64 v[146:147], v[4:5], 1, s[6:7]
	v_mov_b32_e32 v5, v1
	v_readlane_b32 s9, v255, 14
	s_sub_i32 s0, 0xfff, s0
	s_cmp_lg_u32 s32, 0
	s_cselect_b32 s4, 0, 0x80
	s_add_i32 s0, s0, s4
	s_ashr_i32 s4, s0, 31
	v_lshl_add_u64 v[148:149], v[4:5], 1, s[8:9]
	v_lshlrev_b32_e32 v4, 3, v7
	v_ashrrev_i32_e32 v5, 31, v4
	s_lshr_b32 s4, s4, 26
	v_lshl_add_u64 v[150:151], v[4:5], 1, s[6:7]
	v_mov_b32_e32 v5, v1
	s_add_i32 s0, s0, s4
	v_mul_u32_u24_e32 v0, 0xd0, v13
	v_lshl_add_u64 v[152:153], v[4:5], 1, s[8:9]
	v_lshlrev_b32_e32 v4, 1, v49
	s_movk_i32 s6, 0x100
	v_mov_b32_e32 v14, v1
	v_mov_b32_e32 v15, v1
	s_ashr_i32 s0, s0, 6
	v_mul_u32_u24_e32 v199, 0x90, v13
	v_lshlrev_b32_e32 v225, 4, v7
	v_cmp_gt_i32_e64 s[16:17], 8, v7
	v_add3_u32 v226, s6, v0, v4
	v_add_u32_e32 v227, 0x80, v3
	v_add_u32_e32 v228, 0x80, v6
	v_add_u32_e32 v229, 0x80, v2
	v_mov_b32_e32 v0, v1
	v_mov_b32_e32 v2, v1
	v_mov_b32_e32 v3, v1
	v_mov_b32_e32 v4, v1
	v_mov_b32_e32 v6, v1
	v_mov_b32_e32 v7, v1
	v_mov_b32_e32 v8, v1
	v_mov_b32_e32 v9, v1
	v_mov_b32_e32 v10, v1
	v_mov_b32_e32 v11, v1
	v_mov_b32_e32 v12, v1
	v_mov_b32_e32 v13, v1
	v_mov_b64_e32 v[30:31], v[14:15]
	v_mov_b64_e32 v[46:47], v[14:15]
	s_or_b32 s4, s19, 31
	s_cmp_lg_u32 s98, 0
	s_cselect_b32 s4, -1, s4
	s_mov_b32 s5, 0
	s_max_i32 s20, s0, 0
	v_mov_b32_e32 v135, v134
	v_mov_b32_e32 v230, 0
	v_mov_b32_e32 v232, 0xf149f2ca
	v_mov_b64_e32 v[28:29], v[12:13]
	v_mov_b64_e32 v[26:27], v[10:11]
	v_mov_b64_e32 v[24:25], v[8:9]
	v_mov_b64_e32 v[22:23], v[6:7]
	v_mov_b64_e32 v[20:21], v[4:5]
	v_mov_b64_e32 v[18:19], v[2:3]
	v_mov_b64_e32 v[16:17], v[0:1]
	v_mov_b64_e32 v[44:45], v[12:13]
	v_mov_b64_e32 v[42:43], v[10:11]
	v_mov_b64_e32 v[40:41], v[8:9]
	v_mov_b64_e32 v[38:39], v[6:7]
	v_mov_b64_e32 v[36:37], v[4:5]
	v_mov_b64_e32 v[34:35], v[2:3]
	v_mov_b64_e32 v[32:33], v[0:1]
	v_and_b32_e32 v214, 63, v202
	v_and_b32_e32 v215, 3, v214
	v_bfe_u32 v216, v214, 2, 2
	v_bfe_u32 v217, v214, 4, 1
	v_bfe_u32 v218, v214, 5, 1
	v_lshrrev_b32_e32 v219, 1, v215
	v_lshl_or_b32 v219, v217, 1, v219
	v_and_b32_e32 v220, 2, v216
	v_lshl_or_b32 v219, v220, 1, v219
	v_lshlrev_b32_e32 v219, 4, v219
	v_and_b32_e32 v215, 1, v215
	v_lshl_or_b32 v219, v215, 3, v219
	v_lshl_or_b32 v219, v216, 7, v219
	v_lshl_or_b32 v200, v218, 9, v219
	v_xor_b32_e32 v201, 64, v200
	s_mov_b32 s21, 0
	s_and_b32 s8, s21, 1
	s_cmp_gt_i32 s5, s4
	s_cbranch_scc0 .LBB0_156

; #define LAS __attribute__((address_space(3)))
; DI float ex2(float x) { return __builtin_amdgcn_exp2f(x); }
; DI float max3f(float a, float b, float c) { float r; asm("v_max3_f32 %0, %1, %2, %3" : "=v"(r) : "v"(a), "v"(b), "v"(c)); return r; }
; #define MFMA32(a, b, c) __builtin_amdgcn_mfma_f32_32x32x16_bf16((a), (b), (c), 0, 0, 0)
; template <int MODE>
; DI void attn_unit(LAS unsigned char* lds, const AttnArgs a) {
;     ...
;         for (int ks = 0; ks < NKS; ++ks) {
;             const bf16x8 a0 = *(const LAS bf16x8*)(Kc + r32 * KLD + ks * 16 + 8 * hh);
;             const bf16x8 a1 = *(const LAS bf16x8*)(Kc + (32 + r32) * KLD + ks * 16 + 8 * hh);
;             s0 = MFMA32(a0, qf[ks], s0); s1 = MFMA32(a1, qf[ks], s1);
;         }
;         if (MODE == 2) {
;             if (kbase + 63 < q0w) { sb_block<false>(s1, kbase + 32, qi, hh, a.c2, carry); sb_block<false>(s0, kbase, qi, hh, a.c2, carry); }
;             else                  { sb_block<true>(s1, kbase + 32, qi, hh, a.c2, carry);  sb_block<true>(s0, kbase, qi, hh, a.c2, carry); }
;         } else {
;             const bool interior = (MODE == 0) || (MODE == 1 && kbase + 63 <= q0w);
;             float mnew, alpha, ls = 0.f;
;             if (interior) {
; #pragma unroll
;                 for (int i = 0; i < 16; ++i) { s0[i] *= a.c2; s1[i] *= a.c2; }
;                 float mx = max3f(s0[0], s1[0], s0[1]);
;                 mx = max3f(mx, s1[1], s0[2]); mx = max3f(mx, s1[2], s0[3]); mx = max3f(mx, s1[3], s0[4]); mx = max3f(mx, s1[4], s0[5]);
;                 mx = max3f(mx, s1[5], s0[6]); mx = max3f(mx, s1[6], s0[7]); mx = max3f(mx, s1[7], s0[8]); mx = max3f(mx, s1[8], s0[9]);
;                 mx = max3f(mx, s1[9], s0[10]); mx = max3f(mx, s1[10], s0[11]); mx = max3f(mx, s1[11], s0[12]); mx = max3f(mx, s1[12], s0[13]);
;                 mx = max3f(mx, s1[13], s0[14]); mx = max3f(mx, s1[14], s0[15]); mx = fmaxf(mx, s1[15]);
;                 mx = fmaxf(mx, __shfl_xor(mx, 32));
;                 mnew = fmaxf(mrow, mx); alpha = ex2(mrow - mnew);
;     ...
;             mrow = mnew;
;             lrow = lrow * alpha + ls;
;             if (__ballot(alpha < 1.0f) != 0ull) {
; #pragma unroll
;                 for (int d = 0; d < NDB; ++d)
; #pragma unroll
;                     for (int i = 0; i < 16; ++i) o[d][i] *= alpha;
;             }
.LBB0_156:
	s_mul_i32 s9, s8, 0x2c00
	v_lshl_add_u32 v0, s9, 1, v226
	ds_read_b128 v[2:5], v0
	ds_read_b128 v[6:9], v0 offset:6656
	ds_read_b128 v[10:13], v0 offset:32
	ds_read_b128 v[64:67], v0 offset:6688
	ds_read_b128 v[68:71], v0 offset:64
	ds_read_b128 v[72:75], v0 offset:6720
	ds_read_b128 v[76:79], v0 offset:96
	ds_read_b128 v[154:157], v0 offset:6752
	ds_read_b128 v[158:161], v0 offset:128
	ds_read_b128 v[162:165], v0 offset:6784
	ds_read_b128 v[166:169], v0 offset:160
	ds_read_b128 v[170:173], v0 offset:6816
	s_add_i32 s22, s5, 63
	s_mov_b64 s[6:7], -1
	s_cmp_gt_i32 s22, s19
	s_waitcnt lgkmcnt(11)
	v_mfma_f32_32x32x16_bf16 v[48:63], v[2:5], v[96:99], 0
	s_waitcnt lgkmcnt(10)
	v_mfma_f32_32x32x16_bf16 v[80:95], v[6:9], v[96:99], 0
	s_waitcnt lgkmcnt(9)
	v_mfma_f32_32x32x16_bf16 v[48:63], v[10:13], v[100:103], v[48:63]
	s_waitcnt lgkmcnt(8)
	v_mfma_f32_32x32x16_bf16 v[80:95], v[64:67], v[100:103], v[80:95]
	s_waitcnt lgkmcnt(7)
	v_mfma_f32_32x32x16_bf16 v[48:63], v[68:71], v[104:107], v[48:63]
	s_waitcnt lgkmcnt(6)
	v_mfma_f32_32x32x16_bf16 v[80:95], v[72:75], v[104:107], v[80:95]
	s_waitcnt lgkmcnt(5)
	v_mfma_f32_32x32x16_bf16 v[48:63], v[76:79], v[108:111], v[48:63]
	s_waitcnt lgkmcnt(4)
	v_mfma_f32_32x32x16_bf16 v[80:95], v[154:157], v[108:111], v[80:95]
	s_waitcnt lgkmcnt(3)
	v_mfma_f32_32x32x16_bf16 v[48:63], v[158:161], v[112:115], v[48:63]
	s_waitcnt lgkmcnt(2)
	v_mfma_f32_32x32x16_bf16 v[80:95], v[162:165], v[112:115], v[80:95]
	s_waitcnt lgkmcnt(1)
	v_mfma_f32_32x32x16_bf16 v[48:63], v[166:169], v[116:119], v[48:63]
	s_waitcnt lgkmcnt(0)
	v_mfma_f32_32x32x16_bf16 v[80:95], v[170:173], v[116:119], v[80:95]
	s_nop 9
	v_mul_f32_e32 v5, 0x3e16c740, v48
	v_mul_f32_e32 v3, 0x3e16c740, v49
	s_cbranch_scc1 .LBB0_182
	v_max3_f32 v0, v48, v80, v49
	v_max3_f32 v0, v0, v81, v50
	v_max3_f32 v0, v0, v82, v51
	v_max3_f32 v0, v0, v83, v52
	v_max3_f32 v0, v0, v84, v53
	v_max3_f32 v0, v0, v85, v54
	v_max3_f32 v0, v0, v86, v55
	v_max3_f32 v0, v0, v87, v56
	v_max3_f32 v0, v0, v88, v57
	v_max3_f32 v0, v0, v89, v58
	v_max3_f32 v0, v0, v90, v59
	v_max3_f32 v0, v0, v91, v60
	v_max3_f32 v0, v0, v92, v61
	v_max3_f32 v0, v0, v93, v62
	v_max3_f32 v0, v0, v94, v63
	v_and_b32_e32 v4, 64, v243
	v_xor_b32_e32 v5, 32, v243
	v_add_u32_e32 v4, 64, v4
	v_cmp_lt_i32_e32 vcc, v5, v4
	v_max_f32_e32 v0, v0, v95
	v_mul_f32_e32 v0, 0x3e16c740, v0
	v_cndmask_b32_e32 v5, v243, v5, vcc
	v_lshlrev_b32_e32 v5, 2, v5
	ds_bpermute_b32 v3, v5, v0
	s_lshl_b32 s7, s9, 1
	s_mov_b32 s6, 0x3e16c740
	v_add_u32_e32 v158, s7, v200
	v_add_u32_e32 v159, s7, v201
	ds_read_b64_tr_b16 v[64:65], v158 offset:13568
	ds_read_b64_tr_b16 v[66:67], v158 offset:14592
	ds_read_b64_tr_b16 v[68:69], v159 offset:13568
	ds_read_b64_tr_b16 v[70:71], v159 offset:14592
	ds_read_b64_tr_b16 v[72:73], v158 offset:15616
	ds_read_b64_tr_b16 v[74:75], v158 offset:16640
	ds_read_b64_tr_b16 v[76:77], v159 offset:15616
	ds_read_b64_tr_b16 v[78:79], v159 offset:16640
	s_waitcnt lgkmcnt(8)
	v_max3_f32 v231, v232, v0, v3
	v_sub_f32_e32 v2, v232, v231
	v_exp_f32_e32 v2, v2
	v_fma_f32 v48, v48, s6, -v231
	v_fma_f32 v49, v49, s6, -v231
	v_fma_f32 v50, v50, s6, -v231
	v_fma_f32 v51, v51, s6, -v231
	v_fma_f32 v52, v52, s6, -v231
	v_fma_f32 v53, v53, s6, -v231
	v_fma_f32 v54, v54, s6, -v231
	v_fma_f32 v55, v55, s6, -v231
	v_cmp_gt_f32_e32 vcc, 1.0, v2
	s_cbranch_vccz .Lmla_f_nors
	v_pk_mul_f32 v[46:47], v[46:47], v[2:3] op_sel_hi:[1,0]
	v_pk_mul_f32 v[44:45], v[44:45], v[2:3] op_sel_hi:[1,0]
	v_pk_mul_f32 v[42:43], v[42:43], v[2:3] op_sel_hi:[1,0]
	v_pk_mul_f32 v[40:41], v[40:41], v[2:3] op_sel_hi:[1,0]
	v_pk_mul_f32 v[38:39], v[38:39], v[2:3] op_sel_hi:[1,0]
	v_pk_mul_f32 v[36:37], v[36:37], v[2:3] op_sel_hi:[1,0]
	v_pk_mul_f32 v[34:35], v[34:35], v[2:3] op_sel_hi:[1,0]
	v_pk_mul_f32 v[32:33], v[32:33], v[2:3] op_sel_hi:[1,0]
	v_pk_mul_f32 v[30:31], v[30:31], v[2:3] op_sel_hi:[1,0]
	v_pk_mul_f32 v[28:29], v[28:29], v[2:3] op_sel_hi:[1,0]
	v_pk_mul_f32 v[26:27], v[26:27], v[2:3] op_sel_hi:[1,0]
	v_pk_mul_f32 v[24:25], v[24:25], v[2:3] op_sel_hi:[1,0]
	v_pk_mul_f32 v[22:23], v[22:23], v[2:3] op_sel_hi:[1,0]
	v_pk_mul_f32 v[20:21], v[20:21], v[2:3] op_sel_hi:[1,0]
	v_pk_mul_f32 v[18:19], v[18:19], v[2:3] op_sel_hi:[1,0]
	v_pk_mul_f32 v[16:17], v[16:17], v[2:3] op_sel_hi:[1,0]
; template <int MODE>
; DI void attn_unit(LAS unsigned char* lds, const AttnArgs a) {
;     ...
; #pragma unroll
;                 for (int i = 0; i < 16; ++i) {
;                     const float p0 = ex2(s0[i] - mnew), p1 = ex2(s1[i] - mnew);
;                     s0[i] = p0; s1[i] = p1; ls += p0 + p1;
;                 }
;             } else {
;                 float mx = -1e30f;
; #pragma unroll
;                 for (int i = 0; i < 16; ++i) {
;                     const int k0 = kbase + crow(i, hh), k1 = k0 + 32;
;                     float x0 = s0[i] * a.c2, x1 = s1[i] * a.c2;
;                     bool v0 = true, v1 = true;
;                     if (MODE == 1) { v0 = k0 <= qi; v1 = k1 <= qi; }
;                     if (MODE == 3) {
;                         const int st0 = qi - k0, st1 = qi - k1;
;                         v0 = (st0 >= 0) && (st0 <= 128) && (k0 >= 0); v1 = (st1 >= 0) && (st1 <= 128) && (k1 >= 0);
;                         x0 += biasL[min(max(st0, 0), 128)]; x1 += biasL[min(max(st1, 0), 128)];
;                     }
;                     x0 = v0 ? x0 : -1e30f; x1 = v1 ? x1 : -1e30f;
;                     s0[i] = x0; s1[i] = x1; mx = fmaxf(mx, fmaxf(x0, x1));
;                 }
;                 mx = fmaxf(mx, __shfl_xor(mx, 32));
;                 mnew = fmaxf(mrow, mx); alpha = ex2(mrow - mnew);
; #pragma unroll
;                 for (int i = 0; i < 16; ++i) {
;                     const float p0 = (s0[i] > -1e29f) ? ex2(s0[i] - mnew) : 0.f, p1 = (s1[i] > -1e29f) ? ex2(s1[i] - mnew) : 0.f;
;                     s0[i] = p0; s1[i] = p1; ls += p0 + p1;
;                 }
;             }
;             mrow = mnew;
;             lrow = lrow * alpha + ls;
;             if (__ballot(alpha < 1.0f) != 0ull) {
; #pragma unroll
;                 for (int d = 0; d < NDB; ++d)
; #pragma unroll
;                     for (int i = 0; i < 16; ++i) o[d][i] *= alpha;
;             }
;         }
;         const bf16x8 pb00 = pack8(s0, 0), pb01 = pack8(s0, 1), pb10 = pack8(s1, 0), pb11 = pack8(s1, 1);
; #pragma unroll
;         for (int d = 0; d < NDB; ++d) {
;             const LAS bf16_t* vp = Vc + (d * 32 + r32) * VLD;
;             const int sw = SWZ ? ((((d * 32 + r32) >> 3) & 7) << 2) : 0;
;     ...
;             o[d] = MFMA32(VFRAG(0), pb00, o[d]);
;             o[d] = MFMA32(VFRAG(16), pb01, o[d]);
;             o[d] = MFMA32(VFRAG(32), pb10, o[d]);
.Lmla_f_nors:
	v_exp_f32_e32 v48, v48
	v_exp_f32_e32 v49, v49
	v_exp_f32_e32 v50, v50
	v_exp_f32_e32 v51, v51
	v_exp_f32_e32 v52, v52
	v_exp_f32_e32 v53, v53
	v_exp_f32_e32 v54, v54
	v_exp_f32_e32 v55, v55
	v_pk_add_f32 v[160:161], v[48:49], v[50:51]
	v_pk_add_f32 v[160:161], v[160:161], v[52:53]
	v_pk_add_f32 v[160:161], v[160:161], v[54:55]
	v_cvt_pk_bf16_f32 v4, v48, v49
	v_cvt_pk_bf16_f32 v5, v50, v51
	v_cvt_pk_bf16_f32 v6, v52, v53
	v_cvt_pk_bf16_f32 v7, v54, v55
	s_nop 1
	s_waitcnt lgkmcnt(4)
	v_mfma_f32_32x32x16_bf16 v[32:47], v[64:67], v[4:7], v[32:47]
	v_mfma_f32_32x32x16_bf16 v[16:31], v[68:71], v[4:7], v[16:31]
	ds_read_b64_tr_b16 v[64:65], v158 offset:17664
	ds_read_b64_tr_b16 v[66:67], v158 offset:18688
	ds_read_b64_tr_b16 v[68:69], v159 offset:17664
	ds_read_b64_tr_b16 v[70:71], v159 offset:18688
	v_fma_f32 v56, v56, s6, -v231
	v_fma_f32 v57, v57, s6, -v231
	v_fma_f32 v58, v58, s6, -v231
	v_fma_f32 v59, v59, s6, -v231
	v_fma_f32 v60, v60, s6, -v231
	v_fma_f32 v61, v61, s6, -v231
	v_fma_f32 v62, v62, s6, -v231
	v_fma_f32 v63, v63, s6, -v231
	v_exp_f32_e32 v56, v56
	v_exp_f32_e32 v57, v57
	v_exp_f32_e32 v58, v58
	v_exp_f32_e32 v59, v59
	v_exp_f32_e32 v60, v60
	v_exp_f32_e32 v61, v61
	v_exp_f32_e32 v62, v62
	v_exp_f32_e32 v63, v63
	v_pk_add_f32 v[160:161], v[160:161], v[56:57]
	v_pk_add_f32 v[160:161], v[160:161], v[58:59]
	v_pk_add_f32 v[160:161], v[160:161], v[60:61]
	v_pk_add_f32 v[160:161], v[160:161], v[62:63]
	v_cvt_pk_bf16_f32 v8, v56, v57
	v_cvt_pk_bf16_f32 v9, v58, v59
	v_cvt_pk_bf16_f32 v10, v60, v61
	v_cvt_pk_bf16_f32 v11, v62, v63
	s_nop 1
	s_waitcnt lgkmcnt(4)
	v_mfma_f32_32x32x16_bf16 v[32:47], v[72:75], v[8:11], v[32:47]
	v_mfma_f32_32x32x16_bf16 v[16:31], v[76:79], v[8:11], v[16:31]
	ds_read_b64_tr_b16 v[72:73], v158 offset:19712
	ds_read_b64_tr_b16 v[74:75], v158 offset:20736
	ds_read_b64_tr_b16 v[76:77], v159 offset:19712
	ds_read_b64_tr_b16 v[78:79], v159 offset:20736
	v_fma_f32 v80, v80, s6, -v231
	v_fma_f32 v81, v81, s6, -v231
	v_fma_f32 v82, v82, s6, -v231
	v_fma_f32 v83, v83, s6, -v231
	v_fma_f32 v84, v84, s6, -v231
	v_fma_f32 v85, v85, s6, -v231
	v_fma_f32 v86, v86, s6, -v231
	v_fma_f32 v87, v87, s6, -v231
	v_exp_f32_e32 v80, v80
	v_exp_f32_e32 v81, v81
	v_exp_f32_e32 v82, v82
	v_exp_f32_e32 v83, v83
	v_exp_f32_e32 v84, v84
	v_exp_f32_e32 v85, v85
	v_exp_f32_e32 v86, v86
	v_exp_f32_e32 v87, v87
	v_pk_add_f32 v[160:161], v[160:161], v[80:81]
	v_pk_add_f32 v[160:161], v[160:161], v[82:83]
	v_pk_add_f32 v[160:161], v[160:161], v[84:85]
	v_pk_add_f32 v[160:161], v[160:161], v[86:87]
	v_cvt_pk_bf16_f32 v12, v80, v81
	v_cvt_pk_bf16_f32 v13, v82, v83
	v_cvt_pk_bf16_f32 v14, v84, v85
	v_cvt_pk_bf16_f32 v15, v86, v87
	s_nop 1
	s_waitcnt lgkmcnt(4)
	v_mfma_f32_32x32x16_bf16 v[32:47], v[64:67], v[12:15], v[32:47]
	v_mfma_f32_32x32x16_bf16 v[16:31], v[68:71], v[12:15], v[16:31]
	v_fma_f32 v88, v88, s6, -v231
	v_fma_f32 v89, v89, s6, -v231
	v_fma_f32 v90, v90, s6, -v231
	v_fma_f32 v91, v91, s6, -v231
	v_fma_f32 v92, v92, s6, -v231
	v_fma_f32 v93, v93, s6, -v231
	v_fma_f32 v94, v94, s6, -v231
	v_fma_f32 v95, v95, s6, -v231
	v_exp_f32_e32 v88, v88
	v_exp_f32_e32 v89, v89
	v_exp_f32_e32 v90, v90
	v_exp_f32_e32 v91, v91
	v_exp_f32_e32 v92, v92
	v_exp_f32_e32 v93, v93
	v_exp_f32_e32 v94, v94
	v_exp_f32_e32 v95, v95
	v_pk_add_f32 v[160:161], v[160:161], v[88:89]
	v_pk_add_f32 v[160:161], v[160:161], v[90:91]
	v_pk_add_f32 v[160:161], v[160:161], v[92:93]
	v_pk_add_f32 v[160:161], v[160:161], v[94:95]
	v_cvt_pk_bf16_f32 v154, v88, v89
	v_cvt_pk_bf16_f32 v155, v90, v91
	v_cvt_pk_bf16_f32 v156, v92, v93
	v_cvt_pk_bf16_f32 v157, v94, v95
	s_nop 1
	s_waitcnt lgkmcnt(0)
	v_mfma_f32_32x32x16_bf16 v[32:47], v[72:75], v[154:157], v[32:47]
	v_mfma_f32_32x32x16_bf16 v[16:31], v[76:79], v[154:157], v[16:31]
	v_add_f32_e32 v160, v160, v161
	v_fmac_f32_e32 v160, v230, v2
	v_mov_b32_e32 v230, v160
	s_branch .Lmla_pvj

; DI unsigned pk2(float lo, float hi) { f32x2_t v = {lo, hi}; bf16x2_t b = __builtin_convertvector(v, bf16x2_t); return __builtin_bit_cast(unsigned, b); }
; DI float lg2(float x) { return __builtin_amdgcn_logf(x); }
; template <int MODE>
; DI void attn_unit(LAS unsigned char* lds, const AttnArgs a) {
;     ...
;     float inv = 1.f;
;     if (MODE != 2) {
;         const float lt = lrow + __shfl_xor(lrow, 32);
;         inv = 1.0f / lt;
;         if (MODE == 3 && hh == 0) a.lse[qtok * a.ldl] = mrow + lg2(lt);
;     }
; #pragma unroll
;     for (int d = 0; d < NDB; ++d)
; #pragma unroll
;         for (int g4 = 0; g4 < 4; ++g4) {
;             u32x2 w; w.x = pk2(o[d][4 * g4] * inv, o[d][4 * g4 + 1] * inv); w.y = pk2(o[d][4 * g4 + 2] * inv, o[d][4 * g4 + 3] * inv);
;             *(u32x2*)(a.O + qtok * a.ldo + d * 32 + 8 * g4 + 4 * hh) = w;
;         }
.LBB0_186:
	s_cmp_lg_u32 s98, 0
	s_cbranch_scc1 .LBB0_187
	v_and_b32_e32 v2, 64, v243
	v_xor_b32_e32 v0, 32, v243
	v_add_u32_e32 v2, 64, v2
	v_cmp_lt_i32_e32 vcc, v0, v2
	s_lshl_b32 s0, s1, 7
	v_readlane_b32 s1, v255, 15
	v_cndmask_b32_e32 v0, v243, v0, vcc
	v_lshlrev_b32_e32 v0, 2, v0
	ds_bpermute_b32 v0, v0, v230
	s_add_u32 s0, s1, s0
	v_readlane_b32 s1, v255, 16
	s_addc_u32 s1, s1, 0
	v_mov_b32_e32 v143, v1
	s_waitcnt lgkmcnt(0)
	v_add_f32_e32 v0, v230, v0
	v_div_scale_f32 v2, s[4:5], v0, v0, 1.0
	v_rcp_f32_e32 v3, v2
	v_readlane_b32 s12, v255, 21
	v_readlane_b32 s13, v255, 22
	v_fma_f32 v4, -v2, v3, 1.0
	v_fmac_f32_e32 v3, v4, v3
	v_div_scale_f32 v4, vcc, 1.0, v0, 1.0
	v_mul_f32_e32 v5, v4, v3
	v_fma_f32 v6, -v2, v5, v4
	v_fmac_f32_e32 v5, v6, v3
	v_fma_f32 v2, -v2, v5, v4
	v_div_fmas_f32 v2, v2, v3, v5
	v_div_fixup_f32 v0, v2, v0, 1.0
	v_lshlrev_b64 v[2:3], 10, v[132:133]
	v_lshl_add_u64 v[2:3], s[0:1], 0, v[2:3]
	v_pk_mul_f32 v[4:5], v[32:33], v[0:1] op_sel_hi:[1,0]
	v_pk_mul_f32 v[6:7], v[34:35], v[0:1] op_sel_hi:[1,0]
	v_lshl_add_u64 v[2:3], v[142:143], 1, v[2:3]
	v_cvt_pk_bf16_f32 v4, v4, v5
	v_cvt_pk_bf16_f32 v5, v6, v7
	global_store_dwordx2 v[2:3], v[4:5], off
	v_pk_mul_f32 v[4:5], v[36:37], v[0:1] op_sel_hi:[1,0]
	v_pk_mul_f32 v[6:7], v[38:39], v[0:1] op_sel_hi:[1,0]
	v_cvt_pk_bf16_f32 v4, v4, v5
	v_cvt_pk_bf16_f32 v5, v6, v7
	global_store_dwordx2 v[2:3], v[4:5], off offset:16
	v_pk_mul_f32 v[4:5], v[40:41], v[0:1] op_sel_hi:[1,0]
	v_pk_mul_f32 v[6:7], v[42:43], v[0:1] op_sel_hi:[1,0]
	v_cvt_pk_bf16_f32 v4, v4, v5
	v_cvt_pk_bf16_f32 v5, v6, v7
	global_store_dwordx2 v[2:3], v[4:5], off offset:32
	v_pk_mul_f32 v[4:5], v[44:45], v[0:1] op_sel_hi:[1,0]
	v_pk_mul_f32 v[6:7], v[46:47], v[0:1] op_sel_hi:[1,0]
	v_cvt_pk_bf16_f32 v4, v4, v5
	v_cvt_pk_bf16_f32 v5, v6, v7
	global_store_dwordx2 v[2:3], v[4:5], off offset:48
	v_pk_mul_f32 v[4:5], v[16:17], v[0:1] op_sel_hi:[1,0]
	v_pk_mul_f32 v[6:7], v[18:19], v[0:1] op_sel_hi:[1,0]
	v_cvt_pk_bf16_f32 v4, v4, v5
	v_cvt_pk_bf16_f32 v5, v6, v7
	global_store_dwordx2 v[2:3], v[4:5], off offset:64
	v_pk_mul_f32 v[4:5], v[20:21], v[0:1] op_sel_hi:[1,0]
	v_pk_mul_f32 v[6:7], v[22:23], v[0:1] op_sel_hi:[1,0]
	v_cvt_pk_bf16_f32 v4, v4, v5
	v_cvt_pk_bf16_f32 v5, v6, v7
	global_store_dwordx2 v[2:3], v[4:5], off offset:80
	v_pk_mul_f32 v[4:5], v[24:25], v[0:1] op_sel_hi:[1,0]
	v_pk_mul_f32 v[6:7], v[26:27], v[0:1] op_sel_hi:[1,0]
	v_cvt_pk_bf16_f32 v4, v4, v5
	v_cvt_pk_bf16_f32 v5, v6, v7
	global_store_dwordx2 v[2:3], v[4:5], off offset:96
	v_pk_mul_f32 v[4:5], v[28:29], v[0:1] op_sel_hi:[1,0]
	v_pk_mul_f32 v[6:7], v[30:31], v[0:1] op_sel_hi:[1,0]
	v_cvt_pk_bf16_f32 v4, v4, v5
	v_cvt_pk_bf16_f32 v5, v6, v7
	global_store_dwordx2 v[2:3], v[4:5], off offset:112

; __global__ void __launch_bounds__(512, 2) mega(Params p) {
;     extern __shared__ __attribute__((aligned(16))) unsigned char lds_raw[];
	.amdhsa_kernel _Z4mega6Params
		.amdhsa_group_segment_fixed_size 256
		.amdhsa_private_segment_fixed_size 0
		.amdhsa_kernarg_size 504
		.amdhsa_user_sgpr_count 2
		.amdhsa_user_sgpr_dispatch_ptr 0
		.amdhsa_user_sgpr_queue_ptr 0
		.amdhsa_user_sgpr_kernarg_segment_ptr 1
		.amdhsa_user_sgpr_dispatch_id 0
		.amdhsa_user_sgpr_kernarg_preload_length 0
		.amdhsa_user_sgpr_kernarg_preload_offset 0
		.amdhsa_user_sgpr_private_segment_size 0
		.amdhsa_uses_dynamic_stack 0
		.amdhsa_enable_private_segment 0
		.amdhsa_system_sgpr_workgroup_id_x 1
		.amdhsa_system_sgpr_workgroup_id_y 0
		.amdhsa_system_sgpr_workgroup_id_z 0
		.amdhsa_system_sgpr_workgroup_info 0
		.amdhsa_system_vgpr_workitem_id 2
		.amdhsa_next_free_vgpr 256
		.amdhsa_next_free_sgpr 102
		.amdhsa_accum_offset 256
		.amdhsa_reserve_vcc 1
		.amdhsa_float_round_mode_32 0
		.amdhsa_float_round_mode_16_64 0
		.amdhsa_float_denorm_mode_32 3
		.amdhsa_float_denorm_mode_16_64 3
		.amdhsa_dx10_clamp 1
		.amdhsa_ieee_mode 1
		.amdhsa_fp16_overflow 0
		.amdhsa_tg_split 0
		.amdhsa_exception_fp_ieee_invalid_op 0
		.amdhsa_exception_fp_denorm_src 0
		.amdhsa_exception_fp_ieee_div_zero 0
		.amdhsa_exception_fp_ieee_overflow 0
		.amdhsa_exception_fp_ieee_underflow 0
		.amdhsa_exception_fp_ieee_inexact 0
		.amdhsa_exception_int_div_zero 0
	.end_amdhsa_kernel

amdhsa.kernels:
  - .agpr_count:     0
    .args:
      - .offset:         0
        .size:           248
        .value_kind:     by_value
      - .offset:         248
        .size:           4
        .value_kind:     hidden_block_count_x
      - .offset:         252
        .size:           4
        .value_kind:     hidden_block_count_y
      - .offset:         256
        .size:           4
        .value_kind:     hidden_block_count_z
      - .offset:         260
        .size:           2
        .value_kind:     hidden_group_size_x
      - .offset:         262
        .size:           2
        .value_kind:     hidden_group_size_y
      - .offset:         264
        .size:           2
        .value_kind:     hidden_group_size_z
      - .offset:         266
        .size:           2
        .value_kind:     hidden_remainder_x
      - .offset:         268
        .size:           2
        .value_kind:     hidden_remainder_y
      - .offset:         270
        .size:           2
        .value_kind:     hidden_remainder_z
      - .offset:         288
        .size:           8
        .value_kind:     hidden_global_offset_x
      - .offset:         296
        .size:           8
        .value_kind:     hidden_global_offset_y
      - .offset:         304
        .size:           8
        .value_kind:     hidden_global_offset_z
      - .offset:         312
        .size:           2
        .value_kind:     hidden_grid_dims
      - .offset:         336
        .size:           8
        .value_kind:     hidden_multigrid_sync_arg
      - .offset:         368
        .size:           4
        .value_kind:     hidden_dynamic_lds_size
    .group_segment_fixed_size: 256
    .kernarg_segment_align: 8
    .kernarg_segment_size: 504
    .language:       OpenCL C
    .language_version:
      - 2
      - 0
    .max_flat_workgroup_size: 512
    .name:           _Z4mega6Params
    .private_segment_fixed_size: 0
    .sgpr_count:     108
    .sgpr_spill_count: 182
    .symbol:         _Z4mega6Params.kd
    .uniform_work_group_size: 1
    .uses_dynamic_stack: false
    .vgpr_count:     256
    .vgpr_spill_count: 0
    .wavefront_size: 64
